# tail split base plus scalar-base LDS-DMA form in the GEMM K loops
# baseline (speedup 1.0000x reference)
.LBB0_1563:
	ds_read_b128 v[168:171], v165
	ds_read_b128 v[172:175], v165 offset:1024
	ds_read_b128 v[176:179], v165 offset:2048
	ds_read_b128 v[180:183], v165 offset:3072
	ds_read_b128 v[184:187], v166
	ds_read_b128 v[188:191], v166 offset:1024
	ds_read_b128 v[192:195], v166 offset:2048
	ds_read_b128 v[196:199], v166 offset:3072
	s_add_u32 s22, s20, 0xfffc0080
	s_addc_u32 s23, s21, -1
	s_cmp_eq_u32 s49, 12
	s_cselect_b32 s25, s9, s23
	s_cselect_b32 s24, s45, s22
	s_cselect_b32 s23, s11, s48
	s_cselect_b32 s22, s46, s47
	s_add_i32 m0, s17, 0xc000
	ds_read_b128 v[210:213], v167
	ds_read_b128 v[214:217], v167 offset:1024
	ds_read_b128 v[218:221], v167 offset:2048
	ds_read_b128 v[222:225], v167 offset:3072
	ds_read_b128 v[226:229], v167 offset:4096
	ds_read_b128 v[230:233], v167 offset:5120
	ds_read_b128 v[234:237], v167 offset:6144
	ds_read_b128 v[238:241], v167 offset:7168
	global_load_lds_dwordx4 v156, s[20:21]
	s_add_i32 m0, s17, 0xe000
	s_nop 0
	global_load_lds_dwordx4 v154, s[20:21]
	s_waitcnt vmcnt(8)
	s_waitcnt lgkmcnt(0)
	s_barrier
	s_setprio 1
	s_waitcnt lgkmcnt(0)
	v_mfma_f32_16x16x32_bf16 v[124:127], v[168:171], v[210:213], v[124:127]
	v_mfma_f32_16x16x32_bf16 v[116:119], v[176:179], v[210:213], v[116:119]
	v_mfma_f32_16x16x32_bf16 v[108:111], v[168:171], v[218:221], v[108:111]
	v_mfma_f32_16x16x32_bf16 v[100:103], v[176:179], v[218:221], v[100:103]
	v_mfma_f32_16x16x32_bf16 v[92:95], v[168:171], v[226:229], v[92:95]
	v_mfma_f32_16x16x32_bf16 v[84:87], v[176:179], v[226:229], v[84:87]
	v_mfma_f32_16x16x32_bf16 v[76:79], v[168:171], v[234:237], v[76:79]
	v_mfma_f32_16x16x32_bf16 v[68:71], v[176:179], v[234:237], v[68:71]
	v_mfma_f32_16x16x32_bf16 v[124:127], v[172:175], v[214:217], v[124:127]
	v_mfma_f32_16x16x32_bf16 v[116:119], v[180:183], v[214:217], v[116:119]
	v_mfma_f32_16x16x32_bf16 v[108:111], v[172:175], v[222:225], v[108:111]
	v_mfma_f32_16x16x32_bf16 v[100:103], v[180:183], v[222:225], v[100:103]
	v_mfma_f32_16x16x32_bf16 v[92:95], v[172:175], v[230:233], v[92:95]
	v_mfma_f32_16x16x32_bf16 v[84:87], v[180:183], v[230:233], v[84:87]
	v_mfma_f32_16x16x32_bf16 v[76:79], v[172:175], v[238:241], v[76:79]
	v_mfma_f32_16x16x32_bf16 v[68:71], v[180:183], v[238:241], v[68:71]
	s_setprio 0
	s_setprio 1
	v_mfma_f32_16x16x32_bf16 v[120:123], v[184:187], v[210:213], v[120:123]
	v_mfma_f32_16x16x32_bf16 v[112:115], v[192:195], v[210:213], v[112:115]
	v_mfma_f32_16x16x32_bf16 v[104:107], v[184:187], v[218:221], v[104:107]
	v_mfma_f32_16x16x32_bf16 v[96:99], v[192:195], v[218:221], v[96:99]
	v_mfma_f32_16x16x32_bf16 v[88:91], v[184:187], v[226:229], v[88:91]
	v_mfma_f32_16x16x32_bf16 v[80:83], v[192:195], v[226:229], v[80:83]
	v_mfma_f32_16x16x32_bf16 v[72:75], v[184:187], v[234:237], v[72:75]
	v_mfma_f32_16x16x32_bf16 v[64:67], v[192:195], v[234:237], v[64:67]
	v_mfma_f32_16x16x32_bf16 v[120:123], v[188:191], v[214:217], v[120:123]
	v_mfma_f32_16x16x32_bf16 v[112:115], v[196:199], v[214:217], v[112:115]
	v_mfma_f32_16x16x32_bf16 v[104:107], v[188:191], v[222:225], v[104:107]
	v_mfma_f32_16x16x32_bf16 v[96:99], v[196:199], v[222:225], v[96:99]
	v_mfma_f32_16x16x32_bf16 v[88:91], v[188:191], v[230:233], v[88:91]
	v_mfma_f32_16x16x32_bf16 v[80:83], v[196:199], v[230:233], v[80:83]
	v_mfma_f32_16x16x32_bf16 v[72:75], v[188:191], v[238:241], v[72:75]
	v_mfma_f32_16x16x32_bf16 v[64:67], v[196:199], v[238:241], v[64:67]
	s_setprio 0
	s_barrier
	s_add_i32 s50, s43, s33
	s_mov_b32 m0, s50
	s_cmp_lg_u32 s54, 0
	s_cbranch_scc1 .Lts0_skip1
	ds_read_b128 v[210:213], v167 offset:16384
	ds_read_b128 v[214:217], v167 offset:17408
	ds_read_b128 v[218:221], v167 offset:18432
	ds_read_b128 v[222:225], v167 offset:19456
	ds_read_b128 v[226:229], v167 offset:20480
	ds_read_b128 v[230:233], v167 offset:21504
	ds_read_b128 v[234:237], v167 offset:22528
	ds_read_b128 v[238:241], v167 offset:23552
.Lts0_skip1:
	global_load_lds_dwordx4 v132, s[22:23]
	s_add_i32 m0, s50, 0x2000
	s_add_u32 s50, s22, 0x4000
	s_addc_u32 s51, s23, 0
	s_add_i32 s52, s44, s33
	global_load_lds_dwordx4 v128, s[22:23]
	s_mov_b32 m0, s52
	v_lshl_add_u64 v[200:201], s[24:25], 0, v[130:131]
	global_load_lds_dwordx4 v132, s[50:51]
	s_add_i32 m0, s52, 0x2000
	s_nop 0
	global_load_lds_dwordx4 v128, s[50:51]
	v_lshl_add_u64 v[162:163], s[24:25], 0, v[134:135]
	s_mov_b32 m0, s17
	s_nop 0
	global_load_lds_dwordx4 v[162:163], off
	s_mov_b32 m0, s19
	s_nop 0
	global_load_lds_dwordx4 v[200:201], off
	s_waitcnt vmcnt(8)
	s_waitcnt lgkmcnt(0)
	s_barrier
	s_cmp_lg_u32 s54, 0
	s_cbranch_scc1 .Lts0_skip0
	s_setprio 1
	s_waitcnt lgkmcnt(0)
	v_mfma_f32_16x16x32_bf16 v[60:63], v[168:171], v[210:213], v[60:63]
	v_mfma_f32_16x16x32_bf16 v[52:55], v[176:179], v[210:213], v[52:55]
	v_mfma_f32_16x16x32_bf16 v[44:47], v[168:171], v[218:221], v[44:47]
	v_mfma_f32_16x16x32_bf16 v[36:39], v[176:179], v[218:221], v[36:39]
	v_mfma_f32_16x16x32_bf16 v[28:31], v[168:171], v[226:229], v[28:31]
	v_mfma_f32_16x16x32_bf16 v[20:23], v[176:179], v[226:229], v[20:23]
	v_mfma_f32_16x16x32_bf16 v[12:15], v[168:171], v[234:237], v[12:15]
	v_mfma_f32_16x16x32_bf16 v[4:7], v[176:179], v[234:237], v[4:7]
	v_mfma_f32_16x16x32_bf16 v[60:63], v[172:175], v[214:217], v[60:63]
	v_mfma_f32_16x16x32_bf16 v[52:55], v[180:183], v[214:217], v[52:55]
	v_mfma_f32_16x16x32_bf16 v[44:47], v[172:175], v[222:225], v[44:47]
	v_mfma_f32_16x16x32_bf16 v[36:39], v[180:183], v[222:225], v[36:39]
	v_mfma_f32_16x16x32_bf16 v[28:31], v[172:175], v[230:233], v[28:31]
	v_mfma_f32_16x16x32_bf16 v[20:23], v[180:183], v[230:233], v[20:23]
	v_mfma_f32_16x16x32_bf16 v[12:15], v[172:175], v[238:241], v[12:15]
	v_mfma_f32_16x16x32_bf16 v[4:7], v[180:183], v[238:241], v[4:7]
	s_setprio 0
	s_setprio 1
	v_mfma_f32_16x16x32_bf16 v[56:59], v[184:187], v[210:213], v[56:59]
	v_mfma_f32_16x16x32_bf16 v[48:51], v[192:195], v[210:213], v[48:51]
	v_mfma_f32_16x16x32_bf16 v[40:43], v[184:187], v[218:221], v[40:43]
	v_mfma_f32_16x16x32_bf16 v[32:35], v[192:195], v[218:221], v[32:35]
	v_mfma_f32_16x16x32_bf16 v[24:27], v[184:187], v[226:229], v[24:27]
	v_mfma_f32_16x16x32_bf16 v[16:19], v[192:195], v[226:229], v[16:19]
	v_mfma_f32_16x16x32_bf16 v[8:11], v[184:187], v[234:237], v[8:11]
	v_mfma_f32_16x16x32_bf16 v[0:3], v[192:195], v[234:237], v[0:3]
	v_mfma_f32_16x16x32_bf16 v[56:59], v[188:191], v[214:217], v[56:59]
	v_mfma_f32_16x16x32_bf16 v[48:51], v[196:199], v[214:217], v[48:51]
	v_mfma_f32_16x16x32_bf16 v[40:43], v[188:191], v[222:225], v[40:43]
	v_mfma_f32_16x16x32_bf16 v[32:35], v[196:199], v[222:225], v[32:35]
	v_mfma_f32_16x16x32_bf16 v[24:27], v[188:191], v[230:233], v[24:27]
	v_mfma_f32_16x16x32_bf16 v[16:19], v[196:199], v[230:233], v[16:19]
	v_mfma_f32_16x16x32_bf16 v[8:11], v[188:191], v[238:241], v[8:11]
	v_mfma_f32_16x16x32_bf16 v[0:3], v[196:199], v[238:241], v[0:3]
	s_setprio 0
.Lts0_skip0:
	s_barrier
	s_add_i32 s50, 0, 0x18000
	s_add_i32 s51, 0, 0x1c000
	v_add_u32_e32 v180, s50, v164
	v_add_u32_e32 v196, s51, v164
	ds_read_b128 v[168:171], v180
	ds_read_b128 v[172:175], v180 offset:1024
	ds_read_b128 v[176:179], v180 offset:2048
	ds_read_b128 v[180:183], v180 offset:3072
	ds_read_b128 v[184:187], v196
	ds_read_b128 v[188:191], v196 offset:1024
	ds_read_b128 v[192:195], v196 offset:2048
	ds_read_b128 v[196:199], v196 offset:3072
	s_add_u32 s24, s24, 0x40000
	s_addc_u32 s25, s25, 0
	s_mov_b32 m0, s36
	ds_read_b128 v[210:213], v167 offset:32768
	ds_read_b128 v[214:217], v167 offset:33792
	ds_read_b128 v[218:221], v167 offset:34816
	ds_read_b128 v[222:225], v167 offset:35840
	ds_read_b128 v[226:229], v167 offset:36864
	ds_read_b128 v[230:233], v167 offset:37888
	ds_read_b128 v[234:237], v167 offset:38912
	ds_read_b128 v[238:241], v167 offset:39936
	global_load_lds_dwordx4 v134, s[24:25]
	s_mov_b32 m0, s37
	s_nop 0
	global_load_lds_dwordx4 v130, s[24:25]
	s_waitcnt vmcnt(8)
	s_waitcnt lgkmcnt(0)
	s_barrier
	s_setprio 1
	s_waitcnt lgkmcnt(0)
	v_mfma_f32_16x16x32_bf16 v[124:127], v[168:171], v[210:213], v[124:127]
	v_mfma_f32_16x16x32_bf16 v[116:119], v[176:179], v[210:213], v[116:119]
	v_mfma_f32_16x16x32_bf16 v[108:111], v[168:171], v[218:221], v[108:111]
	v_mfma_f32_16x16x32_bf16 v[100:103], v[176:179], v[218:221], v[100:103]
	v_mfma_f32_16x16x32_bf16 v[92:95], v[168:171], v[226:229], v[92:95]
	v_mfma_f32_16x16x32_bf16 v[84:87], v[176:179], v[226:229], v[84:87]
	v_mfma_f32_16x16x32_bf16 v[76:79], v[168:171], v[234:237], v[76:79]
	v_mfma_f32_16x16x32_bf16 v[68:71], v[176:179], v[234:237], v[68:71]
	v_mfma_f32_16x16x32_bf16 v[124:127], v[172:175], v[214:217], v[124:127]
	v_mfma_f32_16x16x32_bf16 v[116:119], v[180:183], v[214:217], v[116:119]
	v_mfma_f32_16x16x32_bf16 v[108:111], v[172:175], v[222:225], v[108:111]
	v_mfma_f32_16x16x32_bf16 v[100:103], v[180:183], v[222:225], v[100:103]
	v_mfma_f32_16x16x32_bf16 v[92:95], v[172:175], v[230:233], v[92:95]
	v_mfma_f32_16x16x32_bf16 v[84:87], v[180:183], v[230:233], v[84:87]
	v_mfma_f32_16x16x32_bf16 v[76:79], v[172:175], v[238:241], v[76:79]
	v_mfma_f32_16x16x32_bf16 v[68:71], v[180:183], v[238:241], v[68:71]
	s_setprio 0
	s_setprio 1
	v_mfma_f32_16x16x32_bf16 v[120:123], v[184:187], v[210:213], v[120:123]
	v_mfma_f32_16x16x32_bf16 v[112:115], v[192:195], v[210:213], v[112:115]
	v_mfma_f32_16x16x32_bf16 v[104:107], v[184:187], v[218:221], v[104:107]
	v_mfma_f32_16x16x32_bf16 v[96:99], v[192:195], v[218:221], v[96:99]
	v_mfma_f32_16x16x32_bf16 v[88:91], v[184:187], v[226:229], v[88:91]
	v_mfma_f32_16x16x32_bf16 v[80:83], v[192:195], v[226:229], v[80:83]
	v_mfma_f32_16x16x32_bf16 v[72:75], v[184:187], v[234:237], v[72:75]
	v_mfma_f32_16x16x32_bf16 v[64:67], v[192:195], v[234:237], v[64:67]
	v_mfma_f32_16x16x32_bf16 v[120:123], v[188:191], v[214:217], v[120:123]
	v_mfma_f32_16x16x32_bf16 v[112:115], v[196:199], v[214:217], v[112:115]
	v_mfma_f32_16x16x32_bf16 v[104:107], v[188:191], v[222:225], v[104:107]
	v_mfma_f32_16x16x32_bf16 v[96:99], v[196:199], v[222:225], v[96:99]
	v_mfma_f32_16x16x32_bf16 v[88:91], v[188:191], v[230:233], v[88:91]
	v_mfma_f32_16x16x32_bf16 v[80:83], v[196:199], v[230:233], v[80:83]
	v_mfma_f32_16x16x32_bf16 v[72:75], v[188:191], v[238:241], v[72:75]
	v_mfma_f32_16x16x32_bf16 v[64:67], v[196:199], v[238:241], v[64:67]
	s_setprio 0
	s_barrier
	s_add_u32 s24, s22, 0x8000
	s_addc_u32 s25, s23, 0
	s_add_i32 s50, s50, s33
	s_mov_b32 m0, s50
	s_cmp_lg_u32 s54, 0
	s_cbranch_scc1 .Lts0_skip3
	ds_read_b128 v[210:213], v167 offset:49152
	ds_read_b128 v[214:217], v167 offset:50176
	ds_read_b128 v[218:221], v167 offset:51200
	ds_read_b128 v[222:225], v167 offset:52224
	ds_read_b128 v[226:229], v167 offset:53248
	ds_read_b128 v[230:233], v167 offset:54272
	ds_read_b128 v[234:237], v167 offset:55296
	ds_read_b128 v[238:241], v167 offset:56320
.Lts0_skip3:
	global_load_lds_dwordx4 v132, s[24:25]
	s_add_i32 m0, s50, 0x2000
	s_add_u32 s22, s22, 0xc000
	v_lshl_add_u64 v[204:205], s[24:25], 0, v[128:129]
	s_addc_u32 s23, s23, 0
	s_add_i32 s24, s51, s33
	global_load_lds_dwordx4 v[204:205], off
	s_mov_b32 m0, s24
	v_lshl_add_u64 v[162:163], v[162:163], 0, s[4:5]
	global_load_lds_dwordx4 v132, s[22:23]
	s_add_i32 m0, s24, 0x2000
	s_nop 0
	global_load_lds_dwordx4 v128, s[22:23]
	s_mov_b32 m0, s40
	s_nop 0
	global_load_lds_dwordx4 v[162:163], off
	v_lshl_add_u64 v[162:163], v[200:201], 0, s[4:5]
	s_mov_b32 m0, s41
	s_nop 0
	global_load_lds_dwordx4 v[162:163], off
	s_waitcnt vmcnt(8)
	s_waitcnt lgkmcnt(0)
	s_barrier
	s_cmp_lg_u32 s54, 0
	s_cbranch_scc1 .Lts0_skip2
	s_setprio 1
	s_waitcnt lgkmcnt(0)
	v_mfma_f32_16x16x32_bf16 v[60:63], v[168:171], v[210:213], v[60:63]
	v_mfma_f32_16x16x32_bf16 v[52:55], v[176:179], v[210:213], v[52:55]
	v_mfma_f32_16x16x32_bf16 v[44:47], v[168:171], v[218:221], v[44:47]
	v_mfma_f32_16x16x32_bf16 v[36:39], v[176:179], v[218:221], v[36:39]
	v_mfma_f32_16x16x32_bf16 v[28:31], v[168:171], v[226:229], v[28:31]
	v_mfma_f32_16x16x32_bf16 v[20:23], v[176:179], v[226:229], v[20:23]
	v_mfma_f32_16x16x32_bf16 v[12:15], v[168:171], v[234:237], v[12:15]
	v_mfma_f32_16x16x32_bf16 v[4:7], v[176:179], v[234:237], v[4:7]
	v_mfma_f32_16x16x32_bf16 v[60:63], v[172:175], v[214:217], v[60:63]
	v_mfma_f32_16x16x32_bf16 v[52:55], v[180:183], v[214:217], v[52:55]
	v_mfma_f32_16x16x32_bf16 v[44:47], v[172:175], v[222:225], v[44:47]
	v_mfma_f32_16x16x32_bf16 v[36:39], v[180:183], v[222:225], v[36:39]
	v_mfma_f32_16x16x32_bf16 v[28:31], v[172:175], v[230:233], v[28:31]
	v_mfma_f32_16x16x32_bf16 v[20:23], v[180:183], v[230:233], v[20:23]
	v_mfma_f32_16x16x32_bf16 v[12:15], v[172:175], v[238:241], v[12:15]
	v_mfma_f32_16x16x32_bf16 v[4:7], v[180:183], v[238:241], v[4:7]
	s_setprio 0
	s_setprio 1
	v_mfma_f32_16x16x32_bf16 v[56:59], v[184:187], v[210:213], v[56:59]
	v_mfma_f32_16x16x32_bf16 v[48:51], v[192:195], v[210:213], v[48:51]
	v_mfma_f32_16x16x32_bf16 v[40:43], v[184:187], v[218:221], v[40:43]
	v_mfma_f32_16x16x32_bf16 v[32:35], v[192:195], v[218:221], v[32:35]
	v_mfma_f32_16x16x32_bf16 v[24:27], v[184:187], v[226:229], v[24:27]
	v_mfma_f32_16x16x32_bf16 v[16:19], v[192:195], v[226:229], v[16:19]
	v_mfma_f32_16x16x32_bf16 v[8:11], v[184:187], v[234:237], v[8:11]
	v_mfma_f32_16x16x32_bf16 v[0:3], v[192:195], v[234:237], v[0:3]
	v_mfma_f32_16x16x32_bf16 v[56:59], v[188:191], v[214:217], v[56:59]
	v_mfma_f32_16x16x32_bf16 v[48:51], v[196:199], v[214:217], v[48:51]
	v_mfma_f32_16x16x32_bf16 v[40:43], v[188:191], v[222:225], v[40:43]
	v_mfma_f32_16x16x32_bf16 v[32:35], v[196:199], v[222:225], v[32:35]
	v_mfma_f32_16x16x32_bf16 v[24:27], v[188:191], v[230:233], v[24:27]
	v_mfma_f32_16x16x32_bf16 v[16:19], v[196:199], v[230:233], v[16:19]
	v_mfma_f32_16x16x32_bf16 v[8:11], v[188:191], v[238:241], v[8:11]
	v_mfma_f32_16x16x32_bf16 v[0:3], v[196:199], v[238:241], v[0:3]
	s_setprio 0
